# first phase boundary uses the kernel's own XCD grid barrier instead of cooperative-groups grid.sync; resid+norm epilogue batched loads/stores
# speedup vs baseline: 1.0203x; 1.0203x over previous
.LBB0_532:
	v_and_b32_e32 v130, 64, v209
	s_lshl_b32 s6, s81, 8
	v_xor_b32_e32 v0, 16, v209
	v_add_u32_e32 v130, 64, v130
	s_add_i32 s6, s6, s47
	v_cmp_lt_i32_e32 vcc, v0, v130
	v_xor_b32_e32 v131, 32, v209
	s_lshl_b32 s0, s34, 5
	v_add_u32_e32 v194, s6, v145
	s_lshl_b32 s6, s84, 8
	v_cndmask_b32_e32 v0, v209, v0, vcc
	v_cmp_lt_i32_e32 vcc, v131, v130
	s_or_b32 s0, s6, s0
	v_ashrrev_i32_e32 v195, 31, v194
	v_cndmask_b32_e32 v130, v209, v131, vcc
	v_lshl_or_b32 v166, v144, 3, s0
	v_lshlrev_b32_e32 v172, 2, v130
	v_lshlrev_b64 v[130:131], 12, v[194:195]
	v_ashrrev_i32_e32 v167, 31, v166
	v_lshl_add_u64 v[130:131], s[16:17], 0, v[130:131]
	v_lshl_add_u64 v[138:139], v[166:167], 2, v[130:131]
	s_barrier
	v_lshlrev_b32_e32 v0, 2, v0
	v_mov_b32_e32 v251, v172
	v_cmp_eq_u32_e32 vcc, 0, v144
	v_lshlrev_b32_e32 v200, 12, v194
	v_lshl_add_u32 v200, v166, 2, v200
	s_lshl_b32 s6, s84, 2
	s_ashr_i32 s7, s6, 31
	s_lshl_b64 s[6:7], s[6:7], 2
	s_add_u32 s0, s22, s6
	s_addc_u32 s7, s23, s7
	s_lshl_b32 s6, s34, 2
	s_add_u32 s6, s0, s6
	s_addc_u32 s7, s7, 0
	v_readlane_b32 s28, v254, 39
	s_mov_b32 s98, s36
	s_mov_b32 s83, 0x800000
	v_readlane_b32 s29, v254, 40
	v_readlane_b32 s48, v254, 41
	s_mov_b64 s[34:35], s[50:51]
	v_readlane_b32 s49, v254, 42
	s_mov_b64 s[8:9], s[16:17]
	global_load_dwordx4 v[150:153], v200, s[8:9]
	global_load_dwordx4 v[146:149], v200, s[8:9] offset:16
	global_load_dwordx4 v[154:157], v200, s[8:9] offset:512
	global_load_dwordx4 v[158:161], v200, s[8:9] offset:528
	s_add_u32 s8, s16, 0x10000
	s_addc_u32 s9, s17, 0
	global_load_dwordx4 v[134:137], v200, s[8:9]
	global_load_dwordx4 v[130:133], v200, s[8:9] offset:16
	global_load_dwordx4 v[138:141], v200, s[8:9] offset:512
	global_load_dwordx4 v[142:145], v200, s[8:9] offset:528
	s_add_u32 s8, s16, 0x20000
	s_addc_u32 s9, s17, 0
	global_load_dwordx4 v[210:213], v200, s[8:9]
	global_load_dwordx4 v[214:217], v200, s[8:9] offset:16
	global_load_dwordx4 v[218:221], v200, s[8:9] offset:512
	global_load_dwordx4 v[222:225], v200, s[8:9] offset:528
	s_add_u32 s8, s16, 0x30000
	s_addc_u32 s9, s17, 0
	global_load_dwordx4 v[226:229], v200, s[8:9]
	global_load_dwordx4 v[230:233], v200, s[8:9] offset:16
	global_load_dwordx4 v[234:237], v200, s[8:9] offset:512
	global_load_dwordx4 v[238:241], v200, s[8:9] offset:528
	s_waitcnt vmcnt(12)
	v_pk_fma_f32 v[150:151], s[18:19], v[126:127], v[150:151]
	v_pk_fma_f32 v[152:153], s[24:25], v[128:129], v[152:153]
	v_pk_fma_f32 v[146:147], s[18:19], v[122:123], v[146:147]
	v_pk_fma_f32 v[148:149], s[24:25], v[124:125], v[148:149]
	v_pk_fma_f32 v[154:155], s[18:19], v[118:119], v[154:155]
	v_pk_fma_f32 v[156:157], s[24:25], v[120:121], v[156:157]
	v_pk_fma_f32 v[158:159], s[18:19], v[114:115], v[158:159]
	v_pk_fma_f32 v[160:161], s[24:25], v[116:117], v[160:161]
	v_mul_f32_e32 v202, v153, v153
	v_mul_f32_e32 v201, v151, v151
	v_fmac_f32_e32 v201, v150, v150
	v_fmac_f32_e32 v202, v152, v152
	v_add_f32_e32 v201, v201, v202
	v_mul_f32_e32 v206, v149, v149
	v_mul_f32_e32 v203, v147, v147
	v_fmac_f32_e32 v203, v146, v146
	v_fmac_f32_e32 v206, v148, v148
	v_add_f32_e32 v203, v203, v206
	v_add_f32_e32 v201, v201, v203
	v_mul_f32_e32 v206, v157, v157
	v_mul_f32_e32 v203, v155, v155
	v_fmac_f32_e32 v203, v154, v154
	v_fmac_f32_e32 v206, v156, v156
	v_add_f32_e32 v203, v203, v206
	v_mul_f32_e32 v206, v161, v161
	v_mul_f32_e32 v202, v159, v159
	v_fmac_f32_e32 v202, v158, v158
	v_fmac_f32_e32 v206, v160, v160
	v_add_f32_e32 v202, v202, v206
	v_add_f32_e32 v203, v203, v202
	v_add_f32_e32 v242, v201, v203
	s_add_u32 s8, s16, 0x80000
	s_addc_u32 s9, s17, 0
	global_load_dwordx4 v[114:117], v200, s[8:9]
	global_load_dwordx4 v[118:121], v200, s[8:9] offset:16
	global_load_dwordx4 v[122:125], v200, s[8:9] offset:512
	global_load_dwordx4 v[126:129], v200, s[8:9] offset:528
	s_waitcnt vmcnt(12)
	v_pk_fma_f32 v[134:135], s[18:19], v[110:111], v[134:135]
	v_pk_fma_f32 v[136:137], s[24:25], v[112:113], v[136:137]
	v_pk_fma_f32 v[130:131], s[18:19], v[106:107], v[130:131]
	v_pk_fma_f32 v[132:133], s[24:25], v[108:109], v[132:133]
	v_pk_fma_f32 v[138:139], s[18:19], v[102:103], v[138:139]
	v_pk_fma_f32 v[140:141], s[24:25], v[104:105], v[140:141]
	v_pk_fma_f32 v[142:143], s[18:19], v[98:99], v[142:143]
	v_pk_fma_f32 v[144:145], s[24:25], v[100:101], v[144:145]
	v_mul_f32_e32 v202, v137, v137
	v_mul_f32_e32 v201, v135, v135
	v_fmac_f32_e32 v201, v134, v134
	v_fmac_f32_e32 v202, v136, v136
	v_add_f32_e32 v201, v201, v202
	v_mul_f32_e32 v206, v133, v133
	v_mul_f32_e32 v203, v131, v131
	v_fmac_f32_e32 v203, v130, v130
	v_fmac_f32_e32 v206, v132, v132
	v_add_f32_e32 v203, v203, v206
	v_add_f32_e32 v201, v201, v203
	v_mul_f32_e32 v206, v141, v141
	v_mul_f32_e32 v203, v139, v139
	v_fmac_f32_e32 v203, v138, v138
	v_fmac_f32_e32 v206, v140, v140
	v_add_f32_e32 v203, v203, v206
	v_mul_f32_e32 v206, v145, v145
	v_mul_f32_e32 v202, v143, v143
	v_fmac_f32_e32 v202, v142, v142
	v_fmac_f32_e32 v206, v144, v144
	v_add_f32_e32 v202, v202, v206
	v_add_f32_e32 v203, v203, v202
	v_add_f32_e32 v243, v201, v203
	s_add_u32 s8, s16, 0x90000
	s_addc_u32 s9, s17, 0
	global_load_dwordx4 v[98:101], v200, s[8:9]
	global_load_dwordx4 v[102:105], v200, s[8:9] offset:16
	global_load_dwordx4 v[106:109], v200, s[8:9] offset:512
	global_load_dwordx4 v[110:113], v200, s[8:9] offset:528
	s_waitcnt vmcnt(12)
	v_pk_fma_f32 v[86:87], s[18:19], v[86:87], v[210:211]
	v_pk_fma_f32 v[88:89], s[24:25], v[88:89], v[212:213]
	v_pk_fma_f32 v[82:83], s[18:19], v[82:83], v[214:215]
	v_pk_fma_f32 v[84:85], s[24:25], v[84:85], v[216:217]
	v_pk_fma_f32 v[90:91], s[18:19], v[90:91], v[218:219]
	v_pk_fma_f32 v[92:93], s[24:25], v[92:93], v[220:221]
	v_pk_fma_f32 v[94:95], s[18:19], v[94:95], v[222:223]
	v_pk_fma_f32 v[96:97], s[24:25], v[96:97], v[224:225]
	v_mul_f32_e32 v202, v89, v89
	v_mul_f32_e32 v201, v87, v87
	v_fmac_f32_e32 v201, v86, v86
	v_fmac_f32_e32 v202, v88, v88
	v_add_f32_e32 v201, v201, v202
	v_mul_f32_e32 v206, v85, v85
	v_mul_f32_e32 v203, v83, v83
	v_fmac_f32_e32 v203, v82, v82
	v_fmac_f32_e32 v206, v84, v84
	v_add_f32_e32 v203, v203, v206
	v_add_f32_e32 v201, v201, v203
	v_mul_f32_e32 v206, v93, v93
	v_mul_f32_e32 v203, v91, v91
	v_fmac_f32_e32 v203, v90, v90
	v_fmac_f32_e32 v206, v92, v92
	v_add_f32_e32 v203, v203, v206
	v_mul_f32_e32 v206, v97, v97
	v_mul_f32_e32 v202, v95, v95
	v_fmac_f32_e32 v202, v94, v94
	v_fmac_f32_e32 v206, v96, v96
	v_add_f32_e32 v202, v202, v206
	v_add_f32_e32 v203, v203, v202
	v_add_f32_e32 v244, v201, v203
	s_add_u32 s8, s16, 0xa0000
	s_addc_u32 s9, s17, 0
	global_load_dwordx4 v[210:213], v200, s[8:9]
	global_load_dwordx4 v[214:217], v200, s[8:9] offset:16
	global_load_dwordx4 v[218:221], v200, s[8:9] offset:512
	global_load_dwordx4 v[222:225], v200, s[8:9] offset:528
	s_waitcnt vmcnt(12)
	v_pk_fma_f32 v[70:71], s[18:19], v[70:71], v[226:227]
	v_pk_fma_f32 v[72:73], s[24:25], v[72:73], v[228:229]
	v_pk_fma_f32 v[66:67], s[18:19], v[66:67], v[230:231]
	v_pk_fma_f32 v[68:69], s[24:25], v[68:69], v[232:233]
	v_pk_fma_f32 v[74:75], s[18:19], v[74:75], v[234:235]
	v_pk_fma_f32 v[76:77], s[24:25], v[76:77], v[236:237]
	v_pk_fma_f32 v[78:79], s[18:19], v[78:79], v[238:239]
	v_pk_fma_f32 v[80:81], s[24:25], v[80:81], v[240:241]
	v_mul_f32_e32 v202, v73, v73
	v_mul_f32_e32 v201, v71, v71
	v_fmac_f32_e32 v201, v70, v70
	v_fmac_f32_e32 v202, v72, v72
	v_add_f32_e32 v201, v201, v202
	v_mul_f32_e32 v206, v69, v69
	v_mul_f32_e32 v203, v67, v67
	v_fmac_f32_e32 v203, v66, v66
	v_fmac_f32_e32 v206, v68, v68
	v_add_f32_e32 v203, v203, v206
	v_add_f32_e32 v201, v201, v203
	v_mul_f32_e32 v206, v77, v77
	v_mul_f32_e32 v203, v75, v75
	v_fmac_f32_e32 v203, v74, v74
	v_fmac_f32_e32 v206, v76, v76
	v_add_f32_e32 v203, v203, v206
	v_mul_f32_e32 v206, v81, v81
	v_mul_f32_e32 v202, v79, v79
	v_fmac_f32_e32 v202, v78, v78
	v_fmac_f32_e32 v206, v80, v80
	v_add_f32_e32 v202, v202, v206
	v_add_f32_e32 v203, v203, v202
	v_add_f32_e32 v245, v201, v203
	s_add_u32 s8, s16, 0xb0000
	s_addc_u32 s9, s17, 0
	global_load_dwordx4 v[226:229], v200, s[8:9]
	global_load_dwordx4 v[230:233], v200, s[8:9] offset:16
	global_load_dwordx4 v[234:237], v200, s[8:9] offset:512
	global_load_dwordx4 v[238:241], v200, s[8:9] offset:528
	s_waitcnt vmcnt(12)
	v_pk_fma_f32 v[54:55], s[18:19], v[54:55], v[114:115]
	v_pk_fma_f32 v[56:57], s[24:25], v[56:57], v[116:117]
	v_pk_fma_f32 v[50:51], s[18:19], v[50:51], v[118:119]
	v_pk_fma_f32 v[52:53], s[24:25], v[52:53], v[120:121]
	v_pk_fma_f32 v[58:59], s[18:19], v[58:59], v[122:123]
	v_pk_fma_f32 v[60:61], s[24:25], v[60:61], v[124:125]
	v_pk_fma_f32 v[62:63], s[18:19], v[62:63], v[126:127]
	v_pk_fma_f32 v[64:65], s[24:25], v[64:65], v[128:129]
	v_mul_f32_e32 v202, v57, v57
	v_mul_f32_e32 v201, v55, v55
	v_fmac_f32_e32 v201, v54, v54
	v_fmac_f32_e32 v202, v56, v56
	v_add_f32_e32 v201, v201, v202
	v_mul_f32_e32 v206, v53, v53
	v_mul_f32_e32 v203, v51, v51
	v_fmac_f32_e32 v203, v50, v50
	v_fmac_f32_e32 v206, v52, v52
	v_add_f32_e32 v203, v203, v206
	v_add_f32_e32 v201, v201, v203
	v_mul_f32_e32 v206, v61, v61
	v_mul_f32_e32 v203, v59, v59
	v_fmac_f32_e32 v203, v58, v58
	v_fmac_f32_e32 v206, v60, v60
	v_add_f32_e32 v203, v203, v206
	v_mul_f32_e32 v206, v65, v65
	v_mul_f32_e32 v202, v63, v63
	v_fmac_f32_e32 v202, v62, v62
	v_fmac_f32_e32 v206, v64, v64
	v_add_f32_e32 v202, v202, v206
	v_add_f32_e32 v203, v203, v202
	v_add_f32_e32 v246, v201, v203
	s_waitcnt vmcnt(8)
	v_pk_fma_f32 v[38:39], s[18:19], v[38:39], v[98:99]
	v_pk_fma_f32 v[40:41], s[24:25], v[40:41], v[100:101]
	v_pk_fma_f32 v[34:35], s[18:19], v[34:35], v[102:103]
	v_pk_fma_f32 v[36:37], s[24:25], v[36:37], v[104:105]
	v_pk_fma_f32 v[42:43], s[18:19], v[42:43], v[106:107]
	v_pk_fma_f32 v[44:45], s[24:25], v[44:45], v[108:109]
	v_pk_fma_f32 v[46:47], s[18:19], v[46:47], v[110:111]
	v_pk_fma_f32 v[48:49], s[24:25], v[48:49], v[112:113]
	v_mul_f32_e32 v202, v41, v41
	v_mul_f32_e32 v201, v39, v39
	v_fmac_f32_e32 v201, v38, v38
	v_fmac_f32_e32 v202, v40, v40
	v_add_f32_e32 v201, v201, v202
	v_mul_f32_e32 v206, v37, v37
	v_mul_f32_e32 v203, v35, v35
	v_fmac_f32_e32 v203, v34, v34
	v_fmac_f32_e32 v206, v36, v36
	v_add_f32_e32 v203, v203, v206
	v_add_f32_e32 v201, v201, v203
	v_mul_f32_e32 v206, v45, v45
	v_mul_f32_e32 v203, v43, v43
	v_fmac_f32_e32 v203, v42, v42
	v_fmac_f32_e32 v206, v44, v44
	v_add_f32_e32 v203, v203, v206
	v_mul_f32_e32 v206, v49, v49
	v_mul_f32_e32 v202, v47, v47
	v_fmac_f32_e32 v202, v46, v46
	v_fmac_f32_e32 v206, v48, v48
	v_add_f32_e32 v202, v202, v206
	v_add_f32_e32 v203, v203, v202
	v_add_f32_e32 v247, v201, v203
	s_waitcnt vmcnt(4)
	v_pk_fma_f32 v[22:23], s[18:19], v[22:23], v[210:211]
	v_pk_fma_f32 v[24:25], s[24:25], v[24:25], v[212:213]
	v_pk_fma_f32 v[18:19], s[18:19], v[18:19], v[214:215]
	v_pk_fma_f32 v[20:21], s[24:25], v[20:21], v[216:217]
	v_pk_fma_f32 v[26:27], s[18:19], v[26:27], v[218:219]
	v_pk_fma_f32 v[28:29], s[24:25], v[28:29], v[220:221]
	v_pk_fma_f32 v[30:31], s[18:19], v[30:31], v[222:223]
	v_pk_fma_f32 v[32:33], s[24:25], v[32:33], v[224:225]
	v_mul_f32_e32 v202, v25, v25
	v_mul_f32_e32 v201, v23, v23
	v_fmac_f32_e32 v201, v22, v22
	v_fmac_f32_e32 v202, v24, v24
	v_add_f32_e32 v201, v201, v202
	v_mul_f32_e32 v206, v21, v21
	v_mul_f32_e32 v203, v19, v19
	v_fmac_f32_e32 v203, v18, v18
	v_fmac_f32_e32 v206, v20, v20
	v_add_f32_e32 v203, v203, v206
	v_add_f32_e32 v201, v201, v203
	v_mul_f32_e32 v206, v29, v29
	v_mul_f32_e32 v203, v27, v27
	v_fmac_f32_e32 v203, v26, v26
	v_fmac_f32_e32 v206, v28, v28
	v_add_f32_e32 v203, v203, v206
	v_mul_f32_e32 v206, v33, v33
	v_mul_f32_e32 v202, v31, v31
	v_fmac_f32_e32 v202, v30, v30
	v_fmac_f32_e32 v206, v32, v32
	v_add_f32_e32 v202, v202, v206
	v_add_f32_e32 v203, v203, v202
	v_add_f32_e32 v248, v201, v203
	s_waitcnt vmcnt(0)
	v_pk_fma_f32 v[6:7], s[18:19], v[6:7], v[226:227]
	v_pk_fma_f32 v[8:9], s[24:25], v[8:9], v[228:229]
	v_pk_fma_f32 v[2:3], s[18:19], v[2:3], v[230:231]
	v_pk_fma_f32 v[4:5], s[24:25], v[4:5], v[232:233]
	v_pk_fma_f32 v[10:11], s[18:19], v[10:11], v[234:235]
	v_pk_fma_f32 v[12:13], s[24:25], v[12:13], v[236:237]
	v_pk_fma_f32 v[14:15], s[18:19], v[14:15], v[238:239]
	v_pk_fma_f32 v[16:17], s[24:25], v[16:17], v[240:241]
	v_mul_f32_e32 v202, v9, v9
	v_mul_f32_e32 v201, v7, v7
	v_fmac_f32_e32 v201, v6, v6
	v_fmac_f32_e32 v202, v8, v8
	v_add_f32_e32 v201, v201, v202
	v_mul_f32_e32 v206, v5, v5
	v_mul_f32_e32 v203, v3, v3
	v_fmac_f32_e32 v203, v2, v2
	v_fmac_f32_e32 v206, v4, v4
	v_add_f32_e32 v203, v203, v206
	v_add_f32_e32 v201, v201, v203
	v_mul_f32_e32 v206, v13, v13
	v_mul_f32_e32 v203, v11, v11
	v_fmac_f32_e32 v203, v10, v10
	v_fmac_f32_e32 v206, v12, v12
	v_add_f32_e32 v203, v203, v206
	v_mul_f32_e32 v206, v17, v17
	v_mul_f32_e32 v202, v15, v15
	v_fmac_f32_e32 v202, v14, v14
	v_fmac_f32_e32 v206, v16, v16
	v_add_f32_e32 v202, v202, v206
	v_add_f32_e32 v203, v203, v202
	v_add_f32_e32 v249, v201, v203
	ds_bpermute_b32 v168, v0, v242
	ds_bpermute_b32 v169, v0, v243
	ds_bpermute_b32 v170, v0, v244
	ds_bpermute_b32 v171, v0, v245
	ds_bpermute_b32 v172, v0, v246
	ds_bpermute_b32 v173, v0, v247
	ds_bpermute_b32 v174, v0, v248
	ds_bpermute_b32 v175, v0, v249
	s_waitcnt lgkmcnt(0)
	v_add_f32_e32 v242, v242, v168
	v_add_f32_e32 v243, v243, v169
	v_add_f32_e32 v244, v244, v170
	v_add_f32_e32 v245, v245, v171
	v_add_f32_e32 v246, v246, v172
	v_add_f32_e32 v247, v247, v173
	v_add_f32_e32 v248, v248, v174
	v_add_f32_e32 v249, v249, v175
	ds_bpermute_b32 v168, v251, v242
	ds_bpermute_b32 v169, v251, v243
	ds_bpermute_b32 v170, v251, v244
	ds_bpermute_b32 v171, v251, v245
	ds_bpermute_b32 v172, v251, v246
	ds_bpermute_b32 v173, v251, v247
	ds_bpermute_b32 v174, v251, v248
	ds_bpermute_b32 v175, v251, v249
	v_lshlrev_b32_e32 v201, 6, v194
	v_add_u32_e32 v202, 0x2000, v201
	s_waitcnt lgkmcnt(0)
	v_add_f32_e32 v242, v242, v168
	v_add_f32_e32 v243, v243, v169
	v_add_f32_e32 v244, v244, v170
	v_add_f32_e32 v245, v245, v171
	v_add_f32_e32 v246, v246, v172
	v_add_f32_e32 v247, v247, v173
	v_add_f32_e32 v248, v248, v174
	v_add_f32_e32 v249, v249, v175
	s_and_saveexec_b64 s[8:9], vcc
	global_store_dword v201, v242, s[6:7]
	global_store_dword v201, v243, s[6:7] offset:1024
	global_store_dword v201, v244, s[6:7] offset:2048
	global_store_dword v201, v245, s[6:7] offset:3072
	global_store_dword v202, v246, s[6:7]
	global_store_dword v202, v247, s[6:7] offset:1024
	global_store_dword v202, v248, s[6:7] offset:2048
	global_store_dword v202, v249, s[6:7] offset:3072
	s_or_b64 exec, exec, s[8:9]
	s_getreg_b32 s0, hwreg(HW_REG_XCC_ID, 0, 4)
	s_waitcnt vmcnt(0)
	s_waitcnt lgkmcnt(0)
	s_barrier
	s_mov_b64 s[6:7], exec
	v_readlane_b32 s8, v252, 4
	v_readlane_b32 s9, v252, 5
	s_and_b64 s[8:9], s[6:7], s[8:9]
	s_xor_b64 s[6:7], s[8:9], s[6:7]
	s_mov_b64 exec, s[8:9]
	s_cbranch_execz .LBB0_601
	v_readlane_b32 s8, v253, 9
	s_waitcnt vmcnt(0) expcnt(0) lgkmcnt(0)
	s_and_b32 s0, s0, 15
	v_mov_b32_e32 v0, s8
	ds_read_b32 v99, v0
	v_readlane_b32 s8, v253, 10
	s_waitcnt lgkmcnt(0)
	v_cmp_ne_u32_e32 vcc, 0, v99
	v_mov_b32_e32 v0, s8
	ds_read_b32 v98, v0
	s_cbranch_vccnz .LBB0_564
	s_mov_b32 s14, 1
	s_branch .LBB0_552

.LBB0_601:
	s_or_b64 exec, exec, s[6:7]
	s_mov_b64 s[84:85], s[62:63]
	s_mov_b64 s[80:81], s[60:61]
	s_mov_b64 s[74:75], s[58:59]
	s_mov_b64 s[28:29], s[56:57]
	s_mov_b64 s[14:15], s[54:55]
	s_mov_b64 s[10:11], s[52:53]
	v_readlane_b32 s6, v254, 27
	v_readlane_b32 s7, v254, 28
	v_readlane_b32 s8, v253, 38
	v_readlane_b32 s9, v253, 39
	v_readlane_b32 s48, v253, 56
	v_readlane_b32 s49, v253, 57
	v_readlane_b32 s50, v254, 8
	v_readlane_b32 s51, v254, 9
	v_readlane_b32 s52, v254, 6
	v_readlane_b32 s53, v254, 7
	s_waitcnt lgkmcnt(0)
	s_barrier
	v_bfe_u32 v201, v204, 4, 2
	v_lshlrev_b32_e32 v202, 2, v166
	v_lshlrev_b32_e32 v203, 6, v194
	v_lshl_add_u32 v203, v201, 4, v203
	v_add_u32_e32 v206, 0x2000, v203
	v_xor_b32_e32 v207, 16, v209
	v_xor_b32_e32 v250, 32, v209
	v_lshlrev_b32_e32 v207, 2, v207
	v_lshlrev_b32_e32 v250, 2, v250
	global_load_dwordx4 v[210:213], v203, s[22:23]
	global_load_dwordx4 v[214:217], v203, s[22:23] offset:1024
	global_load_dwordx4 v[218:221], v203, s[22:23] offset:2048
	global_load_dwordx4 v[222:225], v203, s[22:23] offset:3072
	global_load_dwordx4 v[226:229], v206, s[22:23]
	global_load_dwordx4 v[230:233], v206, s[22:23] offset:1024
	global_load_dwordx4 v[234:237], v206, s[22:23] offset:2048
	global_load_dwordx4 v[238:241], v206, s[22:23] offset:3072
	global_load_dwordx4 v[122:125], v202, s[6:7]
	global_load_dwordx4 v[118:121], v202, s[6:7] offset:16
	global_load_dwordx4 v[110:113], v202, s[6:7] offset:512
	global_load_dwordx4 v[106:109], v202, s[6:7] offset:528
	s_and_b64 vcc, exec, s[8:9]
	s_cbranch_vccz .Lrn_g2_done
	global_load_dwordx4 v[114:117], v202, s[48:49]
	global_load_dwordx4 v[126:129], v202, s[48:49] offset:16
	global_load_dwordx4 v[98:101], v202, s[48:49] offset:512
	global_load_dwordx4 v[102:105], v202, s[48:49] offset:528

.LBB0_731:
	v_readlane_b32 s8, v253, 31
	s_add_i32 s0, s8, 1
	s_cmp_ge_i32 s0, s45
	s_mov_b64 s[6:7], -1
	s_cbranch_scc1 .LBB0_10
	s_getreg_b32 s8, hwreg(HW_REG_XCC_ID, 0, 4)
	s_waitcnt vmcnt(0)
	s_waitcnt vmcnt(0)
	s_barrier
	s_mov_b64 s[6:7], exec
	v_readlane_b32 s10, v252, 4
	v_readlane_b32 s11, v252, 5
	s_and_b64 s[10:11], s[6:7], s[10:11]
	s_mov_b64 exec, s[10:11]
	s_cbranch_execz .LBB0_785
	v_readlane_b32 s9, v253, 9
	s_waitcnt vmcnt(0) expcnt(0) lgkmcnt(0)
	s_and_b32 s47, s8, 15
	v_mov_b32_e32 v0, s9
	ds_read_b32 v3, v0
	v_readlane_b32 s9, v253, 10
	s_waitcnt lgkmcnt(0)
	v_cmp_ne_u32_e32 vcc, 0, v3
	v_mov_b32_e32 v0, s9
	ds_read_b32 v2, v0
	s_cbranch_vccnz .LBB0_749
	s_add_u32 s8, s30, 0x10200
	s_addc_u32 s9, s31, 0
	s_add_u32 s10, s30, 0x10400
	s_addc_u32 s11, s31, 0
	s_add_u32 s12, s30, 0x10500
	s_addc_u32 s13, s31, 0
	s_add_u32 s14, s30, 0x10600
	s_addc_u32 s15, s31, 0
	s_add_u32 s16, s30, 0x10700
	s_addc_u32 s17, s31, 0
	s_add_u32 s18, s30, 0x10800
	s_addc_u32 s19, s31, 0
	s_add_u32 s20, s30, 0x10900
	s_addc_u32 s21, s31, 0
	s_add_u32 s22, s30, 0x10a00
	s_addc_u32 s23, s31, 0
	s_add_u32 s24, s30, 0x10b00
	s_addc_u32 s25, s31, 0
	s_add_u32 s28, s30, 0x10c00
	s_addc_u32 s29, s31, 0
	s_add_u32 s34, s30, 0x10d00
	s_addc_u32 s35, s31, 0
	s_add_u32 s36, s30, 0x10e00
	s_addc_u32 s37, s31, 0
	s_add_u32 s38, s30, 0x10f00
	s_addc_u32 s39, s31, 0
	s_add_u32 s40, s30, 0x11000
	s_addc_u32 s41, s31, 0
	s_add_u32 s42, s30, 0x11100
	s_addc_u32 s43, s31, 0
	s_add_u32 s48, s30, 0x11200
	s_addc_u32 s49, s31, 0
	s_add_u32 s50, s30, 0x11300
	s_addc_u32 s51, s31, 0
	s_mov_b32 s58, 1
	s_branch .LBB0_737
